# speedup vs baseline: 1.0068x; 1.0068x over previous
;     __device__ __forceinline__ bf16_t* Ksf() const { return (bf16_t*)(ws + OFF_Ksf); }
;     __device__ __forceinline__ bf16_t* VsfT() const { return (bf16_t*)(ws + OFF_VsfT); }
;     __device__ __forceinline__ bf16_t* Ksb() const { return (bf16_t*)(ws + OFF_Ksb); }
;     __device__ __forceinline__ bf16_t* VsbT() const { return (bf16_t*)(ws + OFF_VsbT); }
; DEV int tid_opaque() { int t = threadIdx.x; asm volatile("" : "+v"(t)); return t; }
; DEV void st_bf4(bf16_t* p, float a, float b, float c, float d) { uint2 w; w.x = pk_bf16(a, b); w.y = pk_bf16(c, d); *(uint2*)p = w; }
; DEV void cache_convert(const Params& p, int l, int vb, int vnb, float* sm) {
;     const int gt = vb * 256 + tid_opaque(), gn = vnb * 256;
;     for (int i = gt; i < 8 * PAST * 96; i += gn) {
;         const int b = i / (PAST * 96), rem = i % (PAST * 96);
;         const float4 v = *(const float4*)(p.cache_fox_k + ((size_t)(l * 8 + b) * PAST * 384) + (size_t)rem * 4);
;         st_bf4(p.Ksf() + (size_t)b * KSP * 384 + (size_t)rem * 4, v.x, v.y, v.z, v.w);
;     }
;     for (int i = gt; i < 8 * PAST * 64; i += gn) {
;         const int b = i / (PAST * 64), rem = i % (PAST * 64);
;         const float4 v = *(const float4*)(p.cache_sb_k + ((size_t)(l * 8 + b) * PAST * 256) + (size_t)rem * 4);
;         st_bf4(p.Ksb() + (size_t)b * KSP * 256 + (size_t)rem * 4, v.x, v.y, v.z, v.w);
;     }
;     for (int i = gt; i < 8 * 48 * 384; i += gn) { const int b = i / (48 * 384), rem = i % (48 * 384); p.Ksf()[(size_t)b * KSP * 384 + (size_t)2064 * 384 + rem] = 0; }
;     for (int i = gt; i < 8 * 48 * 256; i += gn) { const int b = i / (48 * 256), rem = i % (48 * 256); p.Ksb()[(size_t)b * KSP * 256 + (size_t)2064 * 256 + rem] = 0; }
;     for (int i = gt; i < 8 * 384 * 48; i += gn) { const int row = i / 48, c = i % 48; p.VsfT()[(size_t)row * KSP + 2064 + c] = 0; }
;     for (int i = gt; i < 8 * 256 * 48; i += gn) { const int row = i / 48, c = i % 48; p.VsbT()[(size_t)row * KSP + 2064 + c] = 0; }
; __global__ void __launch_bounds__(256, 2) fwd_kernel(Params p) {
;     ...
;         if (ph == 0 || (ph == 8 && bid >= 64)) cache_convert(pq, ph == 0 ? 0 : 1, ph == 0 ? bid : bid - 64, ph == 0 ? nb : nb - 64, (float*)smem);
.LBB0_2708:
	s_andn2_b64 vcc, exec, s[0:1]
	v_readlane_b32 s4, v254, 4
	v_readlane_b32 s5, v254, 5
	s_cbranch_vccnz .LBB0_2750
	s_sub_i32 s2, s78, 64
	s_and_b64 s[0:1], s[94:95], exec
	s_cselect_b32 s6, s78, s2
	s_sub_i32 s2, s4, 64
	v_mov_b32_e32 v0, v186
	s_and_b64 s[0:1], s[94:95], exec
	s_cselect_b32 s7, s4, s2
	s_and_b64 s[0:1], s[94:95], exec
	s_cbranch_scc0 .Lcc_skip
	s_addk_i32 s7, 0xff40
	s_cmp_ge_i32 s6, s7
	s_cselect_b32 s6, 0x10000, s6
.Lcc_skip:
	v_lshl_add_u32 v0, s6, 8, v0
	s_mov_b32 s0, 0x180000
	s_lshl_b32 s8, s7, 8
	v_cmp_gt_i32_e32 vcc, s0, v0
	s_and_saveexec_b64 s[0:1], vcc
	s_movk_i32 s12, 0x300
	s_mov_b32 s13, 0x2aaaaaab
	s_cbranch_execz .LBB0_2712
	s_and_b64 s[2:3], s[94:95], exec
	v_readlane_b32 s2, v254, 1
	s_cselect_b32 s9, 0, 8
	v_readlane_b32 s3, v254, 2
	s_add_u32 s2, s2, 0x1362c000
	s_addc_u32 s3, s3, 0
	s_mov_b64 s[4:5], 0
	v_mov_b32_e32 v1, v0
